# rmsnorm row sums (init_rows, o2): 6-stage ds_bpermute butterfly replaced by exact DPP quad_perm/row_half_mirror/row_mirror + v_permlane16/32_swap stages (no LDS round trips)
# speedup vs baseline: 1.0021x; 1.0021x over previous
; __device__ __forceinline__ void unpack8(const u32x4 w, float (&f)[8]) { f[0] = bflo(w.x); f[1] = bfhi(w.x); f[2] = bflo(w.y); f[3] = bfhi(w.y); f[4] = bflo(w.z); f[5] = bfhi(w.z); f[6] = bflo(w.w); f[7] = bfhi(w.w); }
; __device__ __forceinline__ u32x4 pack8(const float (&f)[8]) { u32x4 w; w.x = pk_bf16(f[0], f[1]); w.y = pk_bf16(f[2], f[3]); w.z = pk_bf16(f[4], f[5]); w.w = pk_bf16(f[6], f[7]); return w; }
; __device__ __forceinline__ float wave_sum(float v) {
; #pragma unroll
;     for (int o = 1; o < 64; o <<= 1) v += __shfl_xor(v, o);
;     return v;
; }
; __device__ __forceinline__ void init_rows(const float* x32, bf16* h16, float* ssp, int gw, int ngw, int lane) {
;     for (int m = gw; m < T; m += ngw) { float s = 0.f;
; #pragma unroll
;         for (int j = 0; j < 4; ++j) { float v[8]; ld8f(x32 + (size_t)m * D + (64 * j + lane) * 8, v); const u32x4 w = pack8(v); *(u32x4*)(h16 + (size_t)m * D + (64 * j + lane) * 8) = w; unpack8(w, v);
; #pragma unroll
;             for (int e = 0; e < 8; ++e) s += v[e] * v[e]; }
;         s = wave_sum(s);
;         if (lane < 32) ssp[(size_t)m * 32 + lane] = (lane == 0) ? s : 0.f; }
; }
.LBB0_131:
	v_add_co_u32_e32 v12, vcc, 0xfffff000, v4
	v_lshl_add_u64 v[20:21], s[88:89], 0, v[2:3]
	s_waitcnt lgkmcnt(0)
	v_addc_co_u32_e32 v13, vcc, -1, v5, vcc
	v_add_co_u32_e32 v16, vcc, 0xfffff010, v4
	global_load_dwordx4 v[12:15], v[12:13], off
	s_nop 0
	v_addc_co_u32_e32 v17, vcc, -1, v5, vcc
	global_load_dwordx4 v[16:19], v[16:17], off
	v_add_co_u32_e32 v22, vcc, s49, v4
	s_waitcnt vmcnt(0) lgkmcnt(0)
	v_cvt_pk_bf16_f32 v12, v12, v13
	v_addc_co_u32_e32 v23, vcc, -1, v5, vcc
	v_add_co_u32_e32 v32, vcc, s47, v20
	v_cvt_pk_bf16_f32 v13, v14, v15
	s_nop 0
	v_addc_co_u32_e32 v33, vcc, 0, v21, vcc
	v_cvt_pk_bf16_f32 v14, v16, v17
	v_cvt_pk_bf16_f32 v15, v18, v19
	v_add_co_u32_e32 v20, vcc, s52, v4
	global_store_dwordx4 v[32:33], v[12:15], off
	s_nop 0
	v_addc_co_u32_e32 v21, vcc, -1, v5, vcc
	global_load_dwordx4 v[16:19], v[22:23], off
	v_lshlrev_b32_e32 v34, 16, v12
	global_load_dwordx4 v[20:23], v[20:21], off
	v_and_b32_e32 v12, 0xffff0000, v12
	v_mul_f32_e32 v12, v12, v12
	v_lshlrev_b32_e32 v35, 16, v13
	v_fmac_f32_e32 v12, v34, v34
	v_and_b32_e32 v13, 0xffff0000, v13
	v_fmac_f32_e32 v12, v35, v35
	v_lshlrev_b32_e32 v36, 16, v14
	v_fmac_f32_e32 v12, v13, v13
	v_and_b32_e32 v14, 0xffff0000, v14
	v_fmac_f32_e32 v12, v36, v36
	v_lshlrev_b32_e32 v37, 16, v15
	v_fmac_f32_e32 v12, v14, v14
	v_and_b32_e32 v15, 0xffff0000, v15
	v_fmac_f32_e32 v12, v37, v37
	v_fmac_f32_e32 v12, v15, v15
	s_waitcnt vmcnt(0) lgkmcnt(0)
	v_cvt_pk_bf16_f32 v16, v16, v17
	v_cvt_pk_bf16_f32 v17, v18, v19
	v_cvt_pk_bf16_f32 v18, v20, v21
	v_cvt_pk_bf16_f32 v19, v22, v23
	global_store_dwordx4 v[32:33], v[16:19], off offset:1024
	global_load_dwordx4 v[20:23], v[4:5], off
	global_load_dwordx4 v[24:27], v[4:5], off offset:16
	v_lshlrev_b32_e32 v13, 16, v16
	v_and_b32_e32 v14, 0xffff0000, v16
	v_fmac_f32_e32 v12, v13, v13
	v_lshlrev_b32_e32 v15, 16, v17
	v_fmac_f32_e32 v12, v14, v14
	v_and_b32_e32 v16, 0xffff0000, v17
	v_fmac_f32_e32 v12, v15, v15
	v_lshlrev_b32_e32 v17, 16, v18
	v_fmac_f32_e32 v12, v16, v16
	v_and_b32_e32 v18, 0xffff0000, v18
	v_fmac_f32_e32 v12, v17, v17
	v_lshlrev_b32_e32 v34, 16, v19
	v_fmac_f32_e32 v12, v18, v18
	v_and_b32_e32 v19, 0xffff0000, v19
	v_fmac_f32_e32 v12, v34, v34
	v_fmac_f32_e32 v12, v19, v19
	s_waitcnt vmcnt(0) lgkmcnt(0)
	v_cvt_pk_bf16_f32 v20, v20, v21
	v_cvt_pk_bf16_f32 v21, v22, v23
	v_cvt_pk_bf16_f32 v22, v24, v25
	v_cvt_pk_bf16_f32 v23, v26, v27
	global_store_dwordx4 v[32:33], v[20:23], off offset:2048
	global_load_dwordx4 v[24:27], v[4:5], off offset:2048
	global_load_dwordx4 v[28:31], v[4:5], off offset:2064
	v_lshlrev_b32_e32 v13, 16, v20
	v_and_b32_e32 v14, 0xffff0000, v20
	v_fmac_f32_e32 v12, v13, v13
	v_lshlrev_b32_e32 v15, 16, v21
	v_fmac_f32_e32 v12, v14, v14
	v_and_b32_e32 v16, 0xffff0000, v21
	v_fmac_f32_e32 v12, v15, v15
	v_lshlrev_b32_e32 v17, 16, v22
	v_fmac_f32_e32 v12, v16, v16
	v_and_b32_e32 v18, 0xffff0000, v22
	v_fmac_f32_e32 v12, v17, v17
	v_lshlrev_b32_e32 v19, 16, v23
	v_fmac_f32_e32 v12, v18, v18
	v_and_b32_e32 v20, 0xffff0000, v23
	v_fmac_f32_e32 v12, v19, v19
	v_fmac_f32_e32 v12, v20, v20
	s_waitcnt vmcnt(0) lgkmcnt(0)
	v_cvt_pk_bf16_f32 v14, v24, v25
	v_lshlrev_b32_e32 v13, 16, v14
	v_cvt_pk_bf16_f32 v15, v26, v27
	v_and_b32_e32 v18, 0xffff0000, v14
	v_fmac_f32_e32 v12, v13, v13
	v_lshlrev_b32_e32 v19, 16, v15
	v_fmac_f32_e32 v12, v18, v18
	v_cvt_pk_bf16_f32 v16, v28, v29
	v_and_b32_e32 v20, 0xffff0000, v15
	v_fmac_f32_e32 v12, v19, v19
	v_lshlrev_b32_e32 v21, 16, v16
	v_fmac_f32_e32 v12, v20, v20
	v_cvt_pk_bf16_f32 v17, v30, v31
	v_and_b32_e32 v22, 0xffff0000, v16
	v_fmac_f32_e32 v12, v21, v21
	v_lshlrev_b32_e32 v23, 16, v17
	v_fmac_f32_e32 v12, v22, v22
	v_and_b32_e32 v24, 0xffff0000, v17
	v_fmac_f32_e32 v12, v23, v23
	v_fmac_f32_e32 v12, v24, v24
	s_nop 1
	v_mov_b32_dpp v13, v12 quad_perm:[1,0,3,2] row_mask:0xf bank_mask:0xf bound_ctrl:1
	global_store_dwordx4 v[32:33], v[14:17], off offset:3072
	s_waitcnt lgkmcnt(0)
	v_add_f32_e32 v12, v12, v13
	s_nop 1
	v_mov_b32_dpp v13, v12 quad_perm:[2,3,0,1] row_mask:0xf bank_mask:0xf bound_ctrl:1
	s_waitcnt lgkmcnt(0)
	v_add_f32_e32 v12, v12, v13
	s_nop 1
	v_mov_b32_dpp v13, v12 row_half_mirror row_mask:0xf bank_mask:0xf bound_ctrl:1
	s_waitcnt lgkmcnt(0)
	v_add_f32_e32 v12, v12, v13
	s_nop 1
	v_mov_b32_dpp v13, v12 row_mirror row_mask:0xf bank_mask:0xf bound_ctrl:1
	s_waitcnt lgkmcnt(0)
	v_add_f32_e32 v12, v12, v13
	v_mov_b32_e32 v13, v12
	s_nop 1
	v_permlane16_swap_b32_e32 v12, v13
	s_waitcnt lgkmcnt(0)
	v_add_f32_e32 v12, v12, v13
	v_mov_b32_e32 v13, v12
	s_nop 1
	v_permlane32_swap_b32_e32 v12, v13
	s_and_saveexec_b64 s[0:1], s[38:39]
	s_cbranch_execz .LBB0_130
	s_waitcnt lgkmcnt(0)
	v_add_f32_e32 v12, v12, v13
	v_cndmask_b32_e64 v14, 0, v12, s[40:41]
	v_lshl_add_u64 v[12:13], s[88:89], 0, v[0:1]
	global_store_dword v[12:13], v14, off
	s_branch .LBB0_130

; __device__ __forceinline__ float bf2f(bf16 b) { return __uint_as_float((unsigned)b << 16); }
; __device__ __forceinline__ bf16 f2bf(float f) { return (bf16)(pk_bf16(f, 0.f) & 0xffffu); }
; __device__ __forceinline__ void o2_phase(const bf16* P, const float* qnorm, const float* kvnorm, const float* rope, bf16* PD, bf16* QN, bf16* KVN, bf16* KPE, int gw, int ngw, int lane) {
;     ...
;     for (int m = gw; m < T; m += ngw) { const int t = m & (SEQ - 1); const bf16* pr = P + (size_t)m * OD_IN_P;
;         { float u[8], acc[8], tmp[8]; unpack8(*(const u32x4*)(pr + lane * 8), u);
; #pragma unroll
;           for (int e = 0; e < 8; ++e) acc[e] = u[e];
;           const int cnt = (t + 1 < win) ? (t + 1) : win;
;           for (int j = 1; j < cnt; ++j) { unpack8(*(const u32x4*)(pr - (size_t)j * OD_IN_P + lane * 8), tmp);
; #pragma unroll
;               for (int e = 0; e < 8; ++e) acc[e] += tmp[e]; }
;           const float ic = 1.0f / (float)cnt;
; #pragma unroll
;           for (int e = 0; e < 8; ++e) acc[e] = acc[e] * ic - u[e];
;           *(u32x4*)(PD + (size_t)m * 512 + lane * 8) = pack8(acc); }
;         { float q[8]; unpack8(*(const u32x4*)(pr + 512 + lane * 8), q); float s = 0.f;
; #pragma unroll
;           for (int e = 0; e < 8; ++e) s += q[e] * q[e];
;           s = wave_sum(s); const float sc = rsqrtf(s * (1.0f / 512.0f) + NORM_EPS);
; #pragma unroll
;           for (int e = 0; e < 8; ++e) q[e] = q[e] * sc * qg[e];
;           *(u32x4*)(QN + (size_t)m * 512 + lane * 8) = pack8(q); }
;         { float q[8]; unpack8(*(const u32x4*)(pr + 1024 + lane * 8), q); float s = 0.f;
; #pragma unroll
;           for (int e = 0; e < 8; ++e) s += q[e] * q[e];
;           s = wave_sum(s); const float sc = rsqrtf(s * (1.0f / 512.0f) + NORM_EPS);
; #pragma unroll
;           for (int e = 0; e < 8; ++e) q[e] = q[e] * sc * kg[e];
;           *(u32x4*)(KVN + (size_t)m * 512 + lane * 8) = pack8(q); }
;         { const int i = lane & 31; const float t1 = bf2f(pr[1536 + i]), t2 = bf2f(pr[1568 + i]); const float cs = rope[(size_t)m * 64 + 2 * i], sn = rope[(size_t)m * 64 + 2 * i + 1];
;           const float o = (lane < 32) ? (t1 * cs - t2 * sn) : (t1 * sn + t2 * cs);
;           KPE[(size_t)m * 64 + lane] = f2bf(o); }
;     }
.LBB0_269:
	s_add_i32 s4, s4, 1
	v_min_u32_e32 v29, s4, v52
	v_cvt_f32_ubyte0_e32 v29, v29
	v_div_scale_f32 v31, s[0:1], v29, v29, 1.0
	v_rcp_f32_e32 v50, v31
	v_div_scale_f32 v51, vcc, 1.0, v29, 1.0
	s_ashr_i32 s35, s34, 31
	v_fma_f32 v59, -v31, v50, 1.0
	v_fmac_f32_e32 v50, v59, v50
	v_mul_f32_e32 v59, v51, v50
	v_fma_f32 v60, -v31, v59, v51
	v_fmac_f32_e32 v59, v60, v50
	v_fma_f32 v31, -v31, v59, v51
	v_div_fmas_f32 v31, v31, v50, v59
	v_div_fixup_f32 v50, v31, v29, 1.0
	v_pk_fma_f32 v[42:43], v[50:51], v[44:45], v[42:43] op_sel_hi:[0,1,1] neg_lo:[0,0,1] neg_hi:[0,0,1]
	v_pk_fma_f32 v[38:39], v[50:51], v[40:41], v[38:39] op_sel_hi:[0,1,1] neg_lo:[0,0,1] neg_hi:[0,0,1]
	v_pk_fma_f32 v[40:41], v[50:51], v[46:47], v[34:35] op_sel_hi:[0,1,1] neg_lo:[0,0,1] neg_hi:[0,0,1]
	v_pk_fma_f32 v[44:45], v[50:51], v[48:49], v[36:37] op_sel_hi:[0,1,1] neg_lo:[0,0,1] neg_hi:[0,0,1]
	s_lshl_b64 s[0:1], s[34:35], 10
	v_cvt_pk_bf16_f32 v34, v42, v43
	v_cvt_pk_bf16_f32 v35, v38, v39
	v_cvt_pk_bf16_f32 v36, v40, v41
	v_cvt_pk_bf16_f32 v37, v44, v45
	v_lshl_add_u64 v[38:39], v[16:17], 0, s[0:1]
	global_store_dwordx4 v[38:39], v[34:37], off
	global_load_dwordx4 v[34:37], v[32:33], off offset:1024
	s_lshl_b64 s[4:5], s[34:35], 8
	s_add_i32 s2, s2, s16
	s_waitcnt vmcnt(0) lgkmcnt(0)
	v_lshlrev_b32_e32 v42, 16, v34
	v_and_b32_e32 v43, 0xffff0000, v34
	v_lshlrev_b32_e32 v38, 16, v37
	v_and_b32_e32 v39, 0xffff0000, v37
	v_lshlrev_b32_e32 v40, 16, v36
	v_and_b32_e32 v41, 0xffff0000, v36
	v_lshlrev_b32_e32 v36, 16, v35
	v_and_b32_e32 v37, 0xffff0000, v35
	v_pk_mul_f32 v[48:49], v[42:43], v[42:43]
	v_pk_mul_f32 v[46:47], v[36:37], v[36:37]
	v_add_f32_e32 v29, v48, v49
	v_add_f32_e32 v29, v46, v29
	v_pk_mul_f32 v[44:45], v[40:41], v[40:41]
	v_add_f32_e32 v29, v47, v29
	v_add_f32_e32 v29, v44, v29
	v_pk_mul_f32 v[34:35], v[38:39], v[38:39]
	v_add_f32_e32 v29, v45, v29
	v_add_f32_e32 v29, v34, v29
	v_add_f32_e32 v29, v35, v29
	s_nop 1
	v_mov_b32_dpp v31, v29 quad_perm:[1,0,3,2] row_mask:0xf bank_mask:0xf bound_ctrl:1
	v_lshl_add_u64 v[44:45], v[18:19], 0, s[0:1]
	v_lshl_add_u64 v[48:49], v[22:23], 0, s[4:5]
	s_waitcnt lgkmcnt(0)
	v_add_f32_e32 v29, v29, v31
	s_nop 1
	v_mov_b32_dpp v31, v29 quad_perm:[2,3,0,1] row_mask:0xf bank_mask:0xf bound_ctrl:1
	s_waitcnt lgkmcnt(0)
	v_add_f32_e32 v29, v29, v31
	s_nop 1
	v_mov_b32_dpp v31, v29 row_half_mirror row_mask:0xf bank_mask:0xf bound_ctrl:1
	s_waitcnt lgkmcnt(0)
	v_add_f32_e32 v29, v29, v31
	s_nop 1
	v_mov_b32_dpp v31, v29 row_mirror row_mask:0xf bank_mask:0xf bound_ctrl:1
	s_waitcnt lgkmcnt(0)
	v_add_f32_e32 v29, v29, v31
	v_mov_b32_e32 v31, v29
	s_nop 1
	v_permlane16_swap_b32_e32 v29, v31
	s_waitcnt lgkmcnt(0)
	v_add_f32_e32 v29, v29, v31
	v_mov_b32_e32 v31, v29
	s_nop 1
	v_permlane32_swap_b32_e32 v29, v31
	s_waitcnt lgkmcnt(0)
	v_add_f32_e32 v29, v29, v31
	v_fmamk_f32 v29, v29, 0x3b000000, v218
	v_mul_f32_e32 v31, 0x4b800000, v29
	v_cmp_gt_f32_e32 vcc, s12, v29
	s_nop 1
	v_cndmask_b32_e32 v29, v29, v31, vcc
	v_rsq_f32_e32 v29, v29
	s_nop 0
	v_mul_f32_e32 v31, 0x45800000, v29
	v_cndmask_b32_e32 v34, v29, v31, vcc
	v_pk_mul_f32 v[42:43], v[34:35], v[42:43] op_sel_hi:[0,1]
	v_pk_mul_f32 v[36:37], v[34:35], v[36:37] op_sel_hi:[0,1]
	v_pk_mul_f32 v[40:41], v[34:35], v[40:41] op_sel_hi:[0,1]
	v_pk_mul_f32 v[34:35], v[34:35], v[38:39] op_sel_hi:[0,1]
	v_pk_mul_f32 v[38:39], v[0:1], v[42:43]
	v_pk_mul_f32 v[36:37], v[2:3], v[36:37]
	v_pk_mul_f32 v[40:41], v[4:5], v[40:41]
	v_pk_mul_f32 v[42:43], v[6:7], v[34:35]
	v_cvt_pk_bf16_f32 v34, v38, v39
	v_cvt_pk_bf16_f32 v35, v36, v37
	v_cvt_pk_bf16_f32 v36, v40, v41
	v_cvt_pk_bf16_f32 v37, v42, v43
	global_store_dwordx4 v[44:45], v[34:37], off
	global_load_dwordx4 v[32:35], v[32:33], off offset:2048
	s_waitcnt vmcnt(0) lgkmcnt(0)
	v_lshlrev_b32_e32 v40, 16, v32
	v_and_b32_e32 v41, 0xffff0000, v32
	v_lshlrev_b32_e32 v36, 16, v35
	v_and_b32_e32 v37, 0xffff0000, v35
	v_lshlrev_b32_e32 v38, 16, v34
	v_and_b32_e32 v39, 0xffff0000, v34
	v_lshlrev_b32_e32 v34, 16, v33
	v_and_b32_e32 v35, 0xffff0000, v33
	v_pk_mul_f32 v[46:47], v[40:41], v[40:41]
	v_pk_mul_f32 v[44:45], v[34:35], v[34:35]
	v_add_f32_e32 v29, v46, v47
	v_add_f32_e32 v29, v44, v29
	v_pk_mul_f32 v[42:43], v[38:39], v[38:39]
	v_add_f32_e32 v29, v45, v29
	v_add_f32_e32 v29, v42, v29
	v_pk_mul_f32 v[32:33], v[36:37], v[36:37]
	v_add_f32_e32 v29, v43, v29
	v_add_f32_e32 v29, v32, v29
	v_add_f32_e32 v29, v33, v29
	s_nop 1
	v_mov_b32_dpp v31, v29 quad_perm:[1,0,3,2] row_mask:0xf bank_mask:0xf bound_ctrl:1
	v_lshl_add_u64 v[42:43], v[20:21], 0, s[0:1]
	s_lshl_b64 s[0:1], s[34:35], 7
	s_add_i32 s34, s34, s16
	s_cmpk_gt_i32 s34, 0x3fff
	s_waitcnt lgkmcnt(0)
	v_add_f32_e32 v29, v29, v31
	s_nop 1
	v_mov_b32_dpp v31, v29 quad_perm:[2,3,0,1] row_mask:0xf bank_mask:0xf bound_ctrl:1
	s_waitcnt lgkmcnt(0)
	v_add_f32_e32 v29, v29, v31
	s_nop 1
	v_mov_b32_dpp v31, v29 row_half_mirror row_mask:0xf bank_mask:0xf bound_ctrl:1
	s_waitcnt lgkmcnt(0)
	v_add_f32_e32 v29, v29, v31
	s_nop 1
	v_mov_b32_dpp v31, v29 row_mirror row_mask:0xf bank_mask:0xf bound_ctrl:1
	s_waitcnt lgkmcnt(0)
	v_add_f32_e32 v29, v29, v31
	v_mov_b32_e32 v31, v29
	s_nop 1
	v_permlane16_swap_b32_e32 v29, v31
	s_waitcnt lgkmcnt(0)
	v_add_f32_e32 v32, v29, v31
	v_mov_b32_e32 v33, v32
	s_nop 1
	v_permlane32_swap_b32_e32 v32, v33
	v_mov_b32_e32 v29, v97
	v_lshl_add_u64 v[44:45], s[36:37], 0, v[28:29]
	v_mov_b32_e32 v31, v97
	v_lshl_add_u64 v[46:47], s[36:37], 0, v[30:31]
	s_waitcnt lgkmcnt(0)
	v_add_f32_e32 v32, v32, v33
	v_fmamk_f32 v32, v32, 0x3b000000, v218
	v_mul_f32_e32 v33, 0x4b800000, v32
	v_cmp_gt_f32_e32 vcc, s12, v32
	s_nop 1
	v_cndmask_b32_e32 v32, v32, v33, vcc
	v_rsq_f32_e32 v32, v32
	s_nop 0
	v_mul_f32_e32 v29, 0x45800000, v32
	v_cndmask_b32_e32 v32, v32, v29, vcc
	v_pk_mul_f32 v[40:41], v[32:33], v[40:41] op_sel_hi:[0,1]
	v_pk_mul_f32 v[34:35], v[32:33], v[34:35] op_sel_hi:[0,1]
	v_pk_mul_f32 v[38:39], v[32:33], v[38:39] op_sel_hi:[0,1]
	v_pk_mul_f32 v[32:33], v[32:33], v[36:37] op_sel_hi:[0,1]
	v_pk_mul_f32 v[36:37], v[8:9], v[40:41]
	v_pk_mul_f32 v[34:35], v[10:11], v[34:35]
	v_pk_mul_f32 v[38:39], v[12:13], v[38:39]
	v_pk_mul_f32 v[40:41], v[14:15], v[32:33]
	v_cvt_pk_bf16_f32 v32, v36, v37
	v_cvt_pk_bf16_f32 v33, v34, v35
	v_cvt_pk_bf16_f32 v34, v38, v39
	v_cvt_pk_bf16_f32 v35, v40, v41
	global_store_dwordx4 v[42:43], v[32:35], off
	global_load_ushort v29, v[46:47], off
	s_nop 0
	global_load_dwordx2 v[32:33], v[48:49], off
	global_load_ushort v31, v[44:45], off offset:3072
	v_lshl_add_u64 v[34:35], v[24:25], 0, s[0:1]
	s_waitcnt vmcnt(0) lgkmcnt(0)
	v_lshlrev_b32_e32 v37, 16, v29
	v_lshlrev_b32_e32 v36, 16, v31
	v_pk_mul_f32 v[38:39], v[32:33], v[36:37]
	v_pk_mul_f32 v[32:33], v[32:33], v[36:37] op_sel:[1,0] op_sel_hi:[0,1]
	v_sub_f32_e32 v29, v38, v39
	v_add_f32_e32 v31, v32, v33
	v_cndmask_b32_e64 v29, v31, v29, s[38:39]
	v_cvt_pk_bf16_f32 v29, v29, s0
	v_readlane_b32 s0, v254, 1
	v_readlane_b32 s1, v254, 2
	global_store_short v[34:35], v29, off
	s_nop 0
	v_lshl_add_u64 v[26:27], v[26:27], 0, s[0:1]
	s_cbranch_scc1 .LBB0_274
